# fox row-max tree without the self-max canonicalisation steps (3 VALU fewer per step)
# baseline (speedup 1.0000x reference)
.LBB0_254:
	v_add_f32_e32 v181, v233, v0
	v_max_f32_e32 v0, v85, v84
	v_max3_f32 v1, v86, v87, v69
	v_max3_f32 v0, v0, v68, v70
	v_max3_f32 v0, v0, v71, v88
	v_max3_f32 v1, v1, v90, v91
	v_max3_f32 v0, v0, v89, v72
	v_max3_f32 v1, v1, v74, v75
	v_max3_f32 v0, v0, v73, v92
	v_max3_f32 v1, v1, v94, v95
	v_max3_f32 v0, v0, v93, v76
	v_max3_f32 v1, v1, v78, v79
	v_max3_f32 v0, v0, v77, v96
	v_max3_f32 v1, v1, v98, v99
	v_max3_f32 v0, v0, v97, v80
	v_max3_f32 v1, v1, v82, v83
	v_max3_f32 v0, v0, v81, v1
	v_mov_b32_e32 v1, v0
	s_nop 1
	v_permlane32_swap_b32_e32 v0, v1
	s_nop 0
	v_max_f32_e32 v0, v1, v0
	v_cmp_lt_f32_e32 vcc, s17, v0
	s_cmp_lg_u64 vcc, 0
	s_cselect_b64 s[54:55], -1, 0
	s_cbranch_vccnz .LBB0_272

.LBB0_259:
	v_add_f32_e32 v233, v181, v0
	v_max_f32_e32 v0, v37, v36
	v_max3_f32 v1, v38, v39, v53
	v_max3_f32 v0, v0, v52, v54
	v_max3_f32 v0, v0, v55, v40
	v_max3_f32 v1, v1, v42, v43
	v_max3_f32 v0, v0, v41, v56
	v_max3_f32 v1, v1, v58, v59
	v_max3_f32 v0, v0, v57, v44
	v_max3_f32 v1, v1, v46, v47
	v_max3_f32 v0, v0, v45, v60
	v_max3_f32 v1, v1, v62, v63
	v_max3_f32 v0, v0, v61, v48
	v_max3_f32 v1, v1, v50, v51
	v_max3_f32 v0, v0, v49, v64
	v_max3_f32 v1, v1, v66, v67
	v_max3_f32 v0, v0, v65, v1
	v_mov_b32_e32 v1, v0
	s_nop 1
	v_permlane32_swap_b32_e32 v0, v1
	s_nop 0
	v_max_f32_e32 v0, v1, v0
	v_cmp_lt_f32_e32 vcc, s17, v0
	s_cmp_lg_u64 vcc, 0
	s_cselect_b64 s[54:55], -1, 0
	s_cbranch_vccnz .LBB0_275
